# seam: one early L2 writeback issued by the 24th local arriver of each XCD
# speedup vs baseline: 1.0025x; 1.0025x over previous
.LBB0_80:
	s_lshl_b32 s3, s3, 6
	s_add_i32 s4, s3, 0x500
	s_mov_b32 s5, 0
	s_lshl_b64 s[0:1], s[4:5], 2
	s_add_u32 s0, s38, s0
	s_addc_u32 s1, s39, s1
	v_mov_b32_e32 v1, 1
	v_mov_b64_e32 v[4:5], s[0:1]
	flat_atomic_add v1, v[4:5], v1 sc0
	v_cvt_f32_u32_e32 v3, v2
	v_sub_u32_e32 v4, 0, v2
	v_rcp_iflag_f32_e32 v3, v3
	s_nop 0
	v_mul_f32_e32 v3, 0x4f7ffffe, v3
	v_cvt_u32_f32_e32 v3, v3
	v_mul_lo_u32 v4, v4, v3
	v_mul_hi_u32 v4, v3, v4
	v_add_u32_e32 v3, v3, v4
	s_waitcnt vmcnt(0) lgkmcnt(0)
	v_mul_hi_u32 v3, v1, v3
	v_mul_lo_u32 v5, v3, v2
	v_add_u32_e32 v4, 1, v1
	v_sub_u32_e32 v1, v1, v5
	v_add_u32_e32 v6, 1, v3
	v_cmp_ge_u32_e32 vcc, v1, v2
	v_sub_u32_e32 v5, v1, v2
	s_nop 0
	v_cndmask_b32_e32 v3, v3, v6, vcc
	v_cndmask_b32_e32 v1, v1, v5, vcc
	v_add_u32_e32 v5, 1, v3
	v_cmp_ge_u32_e32 vcc, v1, v2
	s_nop 1
	v_cndmask_b32_e32 v1, v3, v5, vcc
	v_mad_u64_u32 v[2:3], s[0:1], v2, v1, v[2:3]
	v_cmp_ne_u32_e32 vcc, v4, v2
	s_and_saveexec_b64 s[0:1], vcc
	s_xor_b64 s[0:1], exec, s[0:1]
	s_cbranch_execz .LBB0_93
	v_and_b32_e32 v5, 31, v4
	v_cmp_eq_u32_e32 vcc, 24, v5
	s_and_saveexec_b64 s[98:99], vcc
	s_cbranch_execz .Lef_1
	buffer_wbl2 sc1
.Lef_1:
	s_or_b64 exec, exec, s[98:99]
	buffer_inv sc1
	s_add_i32 s4, s3, 0x900
	s_lshl_b64 s[4:5], s[4:5], 2
	s_add_u32 s6, s38, s4
	s_addc_u32 s7, s39, s5
	v_mov_b64_e32 v[2:3], s[6:7]
	flat_load_dword v0, v[2:3] sc1
	s_waitcnt vmcnt(0) lgkmcnt(0)
	v_cmp_eq_u32_e32 vcc, v0, v1
	s_and_saveexec_b64 s[4:5], vcc
	s_cbranch_execz .LBB0_92
	s_mov_b32 s22, 1
	s_mov_b64 s[8:9], 0
	s_branch .LBB0_84

.LBB0_250:
	s_lshl_b32 s20, s33, 6
	s_add_i32 s2, s20, 0x500
	s_mov_b32 s3, 0
	s_lshl_b64 s[0:1], s[2:3], 2
	s_add_u32 s0, s36, s0
	s_addc_u32 s1, s37, s1
	v_mov_b32_e32 v1, 1
	v_mov_b64_e32 v[4:5], s[0:1]
	flat_atomic_add v1, v[4:5], v1 sc0
	v_cvt_f32_u32_e32 v3, v2
	v_sub_u32_e32 v4, 0, v2
	v_rcp_iflag_f32_e32 v3, v3
	s_nop 0
	v_mul_f32_e32 v3, 0x4f7ffffe, v3
	v_cvt_u32_f32_e32 v3, v3
	v_mul_lo_u32 v4, v4, v3
	v_mul_hi_u32 v4, v3, v4
	v_add_u32_e32 v3, v3, v4
	s_waitcnt vmcnt(0) lgkmcnt(0)
	v_mul_hi_u32 v3, v1, v3
	v_mul_lo_u32 v5, v3, v2
	v_add_u32_e32 v4, 1, v1
	v_sub_u32_e32 v1, v1, v5
	v_add_u32_e32 v6, 1, v3
	v_cmp_ge_u32_e32 vcc, v1, v2
	v_sub_u32_e32 v5, v1, v2
	s_nop 0
	v_cndmask_b32_e32 v3, v3, v6, vcc
	v_cndmask_b32_e32 v1, v1, v5, vcc
	v_add_u32_e32 v5, 1, v3
	v_cmp_ge_u32_e32 vcc, v1, v2
	s_nop 1
	v_cndmask_b32_e32 v1, v3, v5, vcc
	v_mad_u64_u32 v[2:3], s[0:1], v2, v1, v[2:3]
	v_cmp_ne_u32_e32 vcc, v4, v2
	s_and_saveexec_b64 s[0:1], vcc
	s_xor_b64 s[0:1], exec, s[0:1]
	s_cbranch_execz .LBB0_263
	v_and_b32_e32 v5, 31, v4
	v_cmp_eq_u32_e32 vcc, 24, v5
	s_and_saveexec_b64 s[98:99], vcc
	s_cbranch_execz .Lef_2
	buffer_wbl2 sc1
.Lef_2:
	s_or_b64 exec, exec, s[98:99]
	buffer_inv sc1
	s_add_i32 s2, s20, 0x900
	s_lshl_b64 s[2:3], s[2:3], 2
	s_add_u32 s4, s36, s2
	s_addc_u32 s5, s37, s3
	v_mov_b64_e32 v[2:3], s[4:5]
	flat_load_dword v0, v[2:3] sc1
	s_waitcnt vmcnt(0) lgkmcnt(0)
	v_cmp_eq_u32_e32 vcc, v0, v1
	s_and_saveexec_b64 s[2:3], vcc
	s_cbranch_execz .LBB0_262
	s_mov_b32 s21, 1
	s_mov_b64 s[6:7], 0
	s_branch .LBB0_254

.LBB0_530:
	s_lshl_b32 s20, s33, 6
	s_add_i32 s2, s20, 0x500
	s_mov_b32 s3, 0
	s_lshl_b64 s[0:1], s[2:3], 2
	s_add_u32 s0, s36, s0
	s_addc_u32 s1, s37, s1
	v_mov_b32_e32 v1, 1
	v_mov_b64_e32 v[4:5], s[0:1]
	flat_atomic_add v3, v[4:5], v1 sc0
	v_cvt_f32_u32_e32 v1, v2
	v_sub_u32_e32 v4, 0, v2
	v_rcp_iflag_f32_e32 v1, v1
	s_nop 0
	v_mul_f32_e32 v1, 0x4f7ffffe, v1
	v_cvt_u32_f32_e32 v1, v1
	v_mul_lo_u32 v4, v4, v1
	v_mul_hi_u32 v4, v1, v4
	v_add_u32_e32 v1, v1, v4
	s_waitcnt vmcnt(0) lgkmcnt(0)
	v_mul_hi_u32 v1, v3, v1
	v_mul_lo_u32 v4, v1, v2
	v_sub_u32_e32 v4, v3, v4
	v_cmp_ge_u32_e32 vcc, v4, v2
	v_add_u32_e32 v5, 1, v1
	s_nop 0
	v_cndmask_b32_e32 v1, v1, v5, vcc
	v_sub_u32_e32 v5, v4, v2
	v_cndmask_b32_e32 v4, v4, v5, vcc
	v_cmp_ge_u32_e32 vcc, v4, v2
	v_add_u32_e32 v4, 1, v1
	s_nop 0
	v_cndmask_b32_e32 v1, v1, v4, vcc
	v_add_u32_e32 v4, 1, v3
	v_mad_u64_u32 v[2:3], s[0:1], v2, v1, v[2:3]
	v_cmp_ne_u32_e32 vcc, v4, v2
	s_and_saveexec_b64 s[0:1], vcc
	s_xor_b64 s[0:1], exec, s[0:1]
	s_cbranch_execz .LBB0_543
	v_and_b32_e32 v5, 31, v4
	v_cmp_eq_u32_e32 vcc, 24, v5
	s_and_saveexec_b64 s[98:99], vcc
	s_cbranch_execz .Lef_3
	buffer_wbl2 sc1

.LBB0_1037:
	s_lshl_b32 s20, s33, 6
	s_add_i32 s2, s20, 0x500
	s_mov_b32 s3, 0
	s_lshl_b64 s[0:1], s[2:3], 2
	s_add_u32 s0, s34, s0
	s_addc_u32 s1, s35, s1
	v_mov_b32_e32 v1, 1
	v_mov_b64_e32 v[4:5], s[0:1]
	flat_atomic_add v3, v[4:5], v1 sc0
	v_cvt_f32_u32_e32 v1, v2
	v_sub_u32_e32 v4, 0, v2
	v_rcp_iflag_f32_e32 v1, v1
	s_nop 0
	v_mul_f32_e32 v1, 0x4f7ffffe, v1
	v_cvt_u32_f32_e32 v1, v1
	v_mul_lo_u32 v4, v4, v1
	v_mul_hi_u32 v4, v1, v4
	v_add_u32_e32 v1, v1, v4
	s_waitcnt vmcnt(0) lgkmcnt(0)
	v_mul_hi_u32 v1, v3, v1
	v_mul_lo_u32 v4, v1, v2
	v_sub_u32_e32 v4, v3, v4
	v_cmp_ge_u32_e32 vcc, v4, v2
	v_add_u32_e32 v5, 1, v1
	s_nop 0
	v_cndmask_b32_e32 v1, v1, v5, vcc
	v_sub_u32_e32 v5, v4, v2
	v_cndmask_b32_e32 v4, v4, v5, vcc
	v_cmp_ge_u32_e32 vcc, v4, v2
	v_add_u32_e32 v4, 1, v1
	s_nop 0
	v_cndmask_b32_e32 v1, v1, v4, vcc
	v_add_u32_e32 v4, 1, v3
	v_mad_u64_u32 v[2:3], s[0:1], v2, v1, v[2:3]
	v_cmp_ne_u32_e32 vcc, v4, v2
	s_and_saveexec_b64 s[0:1], vcc
	s_xor_b64 s[0:1], exec, s[0:1]
	s_cbranch_execz .LBB0_1050
	v_and_b32_e32 v5, 31, v4
	v_cmp_eq_u32_e32 vcc, 24, v5
	s_and_saveexec_b64 s[98:99], vcc
	s_cbranch_execz .Lef_6
	buffer_wbl2 sc1
.Lef_6:
	s_or_b64 exec, exec, s[98:99]
	buffer_inv sc1
	s_add_i32 s2, s20, 0x900
	s_lshl_b64 s[2:3], s[2:3], 2
	s_add_u32 s4, s34, s2
	s_addc_u32 s5, s35, s3
	v_mov_b64_e32 v[2:3], s[4:5]
	flat_load_dword v0, v[2:3] sc1
	s_waitcnt vmcnt(0) lgkmcnt(0)
	v_cmp_eq_u32_e32 vcc, v0, v1
	s_and_saveexec_b64 s[2:3], vcc
	s_cbranch_execz .LBB0_1049
	s_mov_b32 s21, 1
	s_mov_b64 s[6:7], 0
	s_branch .LBB0_1041

.LBB0_1286:
	s_lshl_b32 s20, s33, 6
	s_add_i32 s2, s20, 0x500
	s_mov_b32 s3, 0
	s_lshl_b64 s[0:1], s[2:3], 2
	s_add_u32 s0, s34, s0
	s_addc_u32 s1, s35, s1
	v_mov_b32_e32 v1, 1
	v_mov_b64_e32 v[4:5], s[0:1]
	flat_atomic_add v1, v[4:5], v1 sc0
	v_cvt_f32_u32_e32 v3, v2
	v_sub_u32_e32 v4, 0, v2
	v_rcp_iflag_f32_e32 v3, v3
	s_nop 0
	v_mul_f32_e32 v3, 0x4f7ffffe, v3
	v_cvt_u32_f32_e32 v3, v3
	v_mul_lo_u32 v4, v4, v3
	v_mul_hi_u32 v4, v3, v4
	v_add_u32_e32 v3, v3, v4
	s_waitcnt vmcnt(0) lgkmcnt(0)
	v_mul_hi_u32 v3, v1, v3
	v_mul_lo_u32 v5, v3, v2
	v_add_u32_e32 v4, 1, v1
	v_sub_u32_e32 v1, v1, v5
	v_add_u32_e32 v6, 1, v3
	v_cmp_ge_u32_e32 vcc, v1, v2
	v_sub_u32_e32 v5, v1, v2
	s_nop 0
	v_cndmask_b32_e32 v3, v3, v6, vcc
	v_cndmask_b32_e32 v1, v1, v5, vcc
	v_add_u32_e32 v5, 1, v3
	v_cmp_ge_u32_e32 vcc, v1, v2
	s_nop 1
	v_cndmask_b32_e32 v1, v3, v5, vcc
	v_mad_u64_u32 v[2:3], s[0:1], v2, v1, v[2:3]
	v_cmp_ne_u32_e32 vcc, v4, v2
	s_and_saveexec_b64 s[0:1], vcc
	s_xor_b64 s[0:1], exec, s[0:1]
	s_cbranch_execz .LBB0_1299
	v_and_b32_e32 v5, 31, v4
	v_cmp_eq_u32_e32 vcc, 24, v5
	s_and_saveexec_b64 s[98:99], vcc
	s_cbranch_execz .Lef_7
	buffer_wbl2 sc1

.LBB0_1559:
	s_lshl_b32 s20, s33, 6
	s_add_i32 s2, s20, 0x500
	s_mov_b32 s3, 0
	s_lshl_b64 s[0:1], s[2:3], 2
	s_add_u32 s0, s38, s0
	s_addc_u32 s1, s39, s1
	v_mov_b32_e32 v1, 1
	v_mov_b64_e32 v[4:5], s[0:1]
	flat_atomic_add v1, v[4:5], v1 sc0
	v_cvt_f32_u32_e32 v3, v2
	v_sub_u32_e32 v4, 0, v2
	v_rcp_iflag_f32_e32 v3, v3
	s_nop 0
	v_mul_f32_e32 v3, 0x4f7ffffe, v3
	v_cvt_u32_f32_e32 v3, v3
	v_mul_lo_u32 v4, v4, v3
	v_mul_hi_u32 v4, v3, v4
	v_add_u32_e32 v3, v3, v4
	s_waitcnt vmcnt(0) lgkmcnt(0)
	v_mul_hi_u32 v3, v1, v3
	v_mul_lo_u32 v5, v3, v2
	v_add_u32_e32 v4, 1, v1
	v_sub_u32_e32 v1, v1, v5
	v_add_u32_e32 v6, 1, v3
	v_cmp_ge_u32_e32 vcc, v1, v2
	v_sub_u32_e32 v5, v1, v2
	s_nop 0
	v_cndmask_b32_e32 v3, v3, v6, vcc
	v_cndmask_b32_e32 v1, v1, v5, vcc
	v_add_u32_e32 v5, 1, v3
	v_cmp_ge_u32_e32 vcc, v1, v2
	s_nop 1
	v_cndmask_b32_e32 v1, v3, v5, vcc
	v_mad_u64_u32 v[2:3], s[0:1], v2, v1, v[2:3]
	v_cmp_ne_u32_e32 vcc, v4, v2
	s_and_saveexec_b64 s[0:1], vcc
	s_xor_b64 s[0:1], exec, s[0:1]
	s_cbranch_execz .LBB0_1572
	v_and_b32_e32 v5, 31, v4
	v_cmp_eq_u32_e32 vcc, 24, v5
	s_and_saveexec_b64 s[98:99], vcc
	s_cbranch_execz .Lef_8
	buffer_wbl2 sc1
.Lef_8:
	s_or_b64 exec, exec, s[98:99]
	buffer_inv sc1
	s_add_i32 s2, s20, 0x900
	s_lshl_b64 s[2:3], s[2:3], 2
	s_add_u32 s4, s38, s2
	s_addc_u32 s5, s39, s3
	v_mov_b64_e32 v[2:3], s[4:5]
	flat_load_dword v0, v[2:3] sc1
	s_waitcnt vmcnt(0) lgkmcnt(0)
	v_cmp_eq_u32_e32 vcc, v0, v1
	s_and_saveexec_b64 s[2:3], vcc
	s_cbranch_execz .LBB0_1571
	s_mov_b32 s21, 1
	s_mov_b64 s[6:7], 0
	s_branch .LBB0_1563

.LBB0_1679:
	s_lshl_b32 s20, s33, 6
	s_add_i32 s2, s20, 0x500
	s_mov_b32 s3, 0
	s_lshl_b64 s[0:1], s[2:3], 2
	s_add_u32 s0, s40, s0
	s_addc_u32 s1, s41, s1
	v_mov_b32_e32 v1, 1
	v_mov_b64_e32 v[4:5], s[0:1]
	flat_atomic_add v1, v[4:5], v1 sc0
	v_cvt_f32_u32_e32 v3, v2
	v_sub_u32_e32 v4, 0, v2
	v_rcp_iflag_f32_e32 v3, v3
	s_nop 0
	v_mul_f32_e32 v3, 0x4f7ffffe, v3
	v_cvt_u32_f32_e32 v3, v3
	v_mul_lo_u32 v4, v4, v3
	v_mul_hi_u32 v4, v3, v4
	v_add_u32_e32 v3, v3, v4
	s_waitcnt vmcnt(0) lgkmcnt(0)
	v_mul_hi_u32 v3, v1, v3
	v_mul_lo_u32 v5, v3, v2
	v_add_u32_e32 v4, 1, v1
	v_sub_u32_e32 v1, v1, v5
	v_add_u32_e32 v6, 1, v3
	v_cmp_ge_u32_e32 vcc, v1, v2
	v_sub_u32_e32 v5, v1, v2
	s_nop 0
	v_cndmask_b32_e32 v3, v3, v6, vcc
	v_cndmask_b32_e32 v1, v1, v5, vcc
	v_add_u32_e32 v5, 1, v3
	v_cmp_ge_u32_e32 vcc, v1, v2
	s_nop 1
	v_cndmask_b32_e32 v1, v3, v5, vcc
	v_mad_u64_u32 v[2:3], s[0:1], v2, v1, v[2:3]
	v_cmp_ne_u32_e32 vcc, v4, v2
	s_and_saveexec_b64 s[0:1], vcc
	s_xor_b64 s[0:1], exec, s[0:1]
	s_cbranch_execz .LBB0_1692
	v_and_b32_e32 v5, 31, v4
	v_cmp_eq_u32_e32 vcc, 24, v5
	s_and_saveexec_b64 s[98:99], vcc
	s_cbranch_execz .Lef_9
	buffer_wbl2 sc1
.Lef_9:
	s_or_b64 exec, exec, s[98:99]
	buffer_inv sc1
	s_add_i32 s2, s20, 0x900
	s_lshl_b64 s[2:3], s[2:3], 2
	s_add_u32 s4, s40, s2
	s_addc_u32 s5, s41, s3
	v_mov_b64_e32 v[2:3], s[4:5]
	flat_load_dword v0, v[2:3] sc1
	s_waitcnt vmcnt(0) lgkmcnt(0)
	v_cmp_eq_u32_e32 vcc, v0, v1
	s_and_saveexec_b64 s[2:3], vcc
	s_cbranch_execz .LBB0_1691
	s_mov_b32 s21, 1
	s_mov_b64 s[6:7], 0
	s_branch .LBB0_1683

.LBB0_1729:
	s_lshl_b32 s22, s33, 6
	s_add_i32 s2, s22, 0x500
	s_mov_b32 s3, 0
	s_lshl_b64 s[0:1], s[2:3], 2
	s_add_u32 s0, s42, s0
	s_addc_u32 s1, s43, s1
	v_mov_b32_e32 v1, 1
	v_mov_b64_e32 v[4:5], s[0:1]
	flat_atomic_add v1, v[4:5], v1 sc0
	v_cvt_f32_u32_e32 v3, v2
	v_sub_u32_e32 v4, 0, v2
	v_rcp_iflag_f32_e32 v3, v3
	s_nop 0
	v_mul_f32_e32 v3, 0x4f7ffffe, v3
	v_cvt_u32_f32_e32 v3, v3
	v_mul_lo_u32 v4, v4, v3
	v_mul_hi_u32 v4, v3, v4
	v_add_u32_e32 v3, v3, v4
	s_waitcnt vmcnt(0) lgkmcnt(0)
	v_mul_hi_u32 v3, v1, v3
	v_mul_lo_u32 v5, v3, v2
	v_add_u32_e32 v4, 1, v1
	v_sub_u32_e32 v1, v1, v5
	v_add_u32_e32 v6, 1, v3
	v_cmp_ge_u32_e32 vcc, v1, v2
	v_sub_u32_e32 v5, v1, v2
	s_nop 0
	v_cndmask_b32_e32 v3, v3, v6, vcc
	v_cndmask_b32_e32 v1, v1, v5, vcc
	v_add_u32_e32 v5, 1, v3
	v_cmp_ge_u32_e32 vcc, v1, v2
	s_nop 1
	v_cndmask_b32_e32 v1, v3, v5, vcc
	v_mad_u64_u32 v[2:3], s[0:1], v2, v1, v[2:3]
	v_cmp_ne_u32_e32 vcc, v4, v2
	s_and_saveexec_b64 s[0:1], vcc
	s_xor_b64 s[0:1], exec, s[0:1]
	s_cbranch_execz .LBB0_1742
	v_and_b32_e32 v5, 31, v4
	v_cmp_eq_u32_e32 vcc, 24, v5
	s_and_saveexec_b64 s[98:99], vcc
	s_cbranch_execz .Lef_10
	buffer_wbl2 sc1
.Lef_10:
	s_or_b64 exec, exec, s[98:99]
	buffer_inv sc1
	s_add_i32 s2, s22, 0x900
	s_lshl_b64 s[2:3], s[2:3], 2
	s_add_u32 s4, s42, s2
	s_addc_u32 s5, s43, s3
	v_mov_b64_e32 v[2:3], s[4:5]
	flat_load_dword v0, v[2:3] sc1
	s_waitcnt vmcnt(0) lgkmcnt(0)
	v_cmp_eq_u32_e32 vcc, v0, v1
	s_and_saveexec_b64 s[2:3], vcc
	s_cbranch_execz .LBB0_1741
	s_mov_b32 s23, 1
	s_mov_b64 s[8:9], 0
	s_branch .LBB0_1733

.LBB0_1801:
	s_lshl_b32 s22, s33, 6
	s_add_i32 s2, s22, 0x500
	s_mov_b32 s3, 0
	s_lshl_b64 s[0:1], s[2:3], 2
	s_add_u32 s0, s40, s0
	s_addc_u32 s1, s41, s1
	v_mov_b32_e32 v1, 1
	v_mov_b64_e32 v[4:5], s[0:1]
	flat_atomic_add v1, v[4:5], v1 sc0
	v_cvt_f32_u32_e32 v3, v2
	v_sub_u32_e32 v4, 0, v2
	v_rcp_iflag_f32_e32 v3, v3
	s_nop 0
	v_mul_f32_e32 v3, 0x4f7ffffe, v3
	v_cvt_u32_f32_e32 v3, v3
	v_mul_lo_u32 v4, v4, v3
	v_mul_hi_u32 v4, v3, v4
	v_add_u32_e32 v3, v3, v4
	s_waitcnt vmcnt(0) lgkmcnt(0)
	v_mul_hi_u32 v3, v1, v3
	v_mul_lo_u32 v5, v3, v2
	v_add_u32_e32 v4, 1, v1
	v_sub_u32_e32 v1, v1, v5
	v_add_u32_e32 v6, 1, v3
	v_cmp_ge_u32_e32 vcc, v1, v2
	v_sub_u32_e32 v5, v1, v2
	s_nop 0
	v_cndmask_b32_e32 v3, v3, v6, vcc
	v_cndmask_b32_e32 v1, v1, v5, vcc
	v_add_u32_e32 v5, 1, v3
	v_cmp_ge_u32_e32 vcc, v1, v2
	s_nop 1
	v_cndmask_b32_e32 v1, v3, v5, vcc
	v_mad_u64_u32 v[2:3], s[0:1], v2, v1, v[2:3]
	v_cmp_ne_u32_e32 vcc, v4, v2
	s_and_saveexec_b64 s[0:1], vcc
	s_xor_b64 s[0:1], exec, s[0:1]
	s_cbranch_execz .LBB0_1814
	v_and_b32_e32 v5, 31, v4
	v_cmp_eq_u32_e32 vcc, 24, v5
	s_and_saveexec_b64 s[98:99], vcc
	s_cbranch_execz .Lef_11
	buffer_wbl2 sc1
.Lef_11:
	s_or_b64 exec, exec, s[98:99]
	buffer_inv sc1
	s_add_i32 s2, s22, 0x900
	s_lshl_b64 s[2:3], s[2:3], 2
	s_add_u32 s4, s40, s2
	s_addc_u32 s5, s41, s3
	v_mov_b64_e32 v[2:3], s[4:5]
	flat_load_dword v0, v[2:3] sc1
	s_waitcnt vmcnt(0) lgkmcnt(0)
	v_cmp_eq_u32_e32 vcc, v0, v1
	s_and_saveexec_b64 s[2:3], vcc
	s_cbranch_execz .LBB0_1813
	s_mov_b32 s23, 1
	s_mov_b64 s[8:9], 0
	s_branch .LBB0_1805

.LBB0_1921:
	s_lshl_b32 s22, s91, 6
	s_add_i32 s2, s22, 0x500
	s_mov_b32 s3, 0
	s_lshl_b64 s[0:1], s[2:3], 2
	s_add_u32 s0, s76, s0
	s_addc_u32 s1, s77, s1
	v_mov_b32_e32 v1, 1
	v_mov_b64_e32 v[4:5], s[0:1]
	flat_atomic_add v1, v[4:5], v1 sc0
	v_cvt_f32_u32_e32 v3, v2
	v_sub_u32_e32 v4, 0, v2
	v_rcp_iflag_f32_e32 v3, v3
	s_nop 0
	v_mul_f32_e32 v3, 0x4f7ffffe, v3
	v_cvt_u32_f32_e32 v3, v3
	v_mul_lo_u32 v4, v4, v3
	v_mul_hi_u32 v4, v3, v4
	v_add_u32_e32 v3, v3, v4
	s_waitcnt vmcnt(0) lgkmcnt(0)
	v_mul_hi_u32 v3, v1, v3
	v_mul_lo_u32 v5, v3, v2
	v_add_u32_e32 v4, 1, v1
	v_sub_u32_e32 v1, v1, v5
	v_add_u32_e32 v6, 1, v3
	v_cmp_ge_u32_e32 vcc, v1, v2
	v_sub_u32_e32 v5, v1, v2
	s_nop 0
	v_cndmask_b32_e32 v3, v3, v6, vcc
	v_cndmask_b32_e32 v1, v1, v5, vcc
	v_add_u32_e32 v5, 1, v3
	v_cmp_ge_u32_e32 vcc, v1, v2
	s_nop 1
	v_cndmask_b32_e32 v1, v3, v5, vcc
	v_mad_u64_u32 v[2:3], s[0:1], v2, v1, v[2:3]
	v_cmp_ne_u32_e32 vcc, v4, v2
	s_and_saveexec_b64 s[0:1], vcc
	s_xor_b64 s[0:1], exec, s[0:1]
	s_cbranch_execz .LBB0_1934
	v_and_b32_e32 v5, 31, v4
	v_cmp_eq_u32_e32 vcc, 24, v5
	s_and_saveexec_b64 s[98:99], vcc
	s_cbranch_execz .Lef_12
	buffer_wbl2 sc1
.Lef_12:
	s_or_b64 exec, exec, s[98:99]
	buffer_inv sc1
	s_add_i32 s2, s22, 0x900
	s_lshl_b64 s[2:3], s[2:3], 2
	s_add_u32 s4, s76, s2
	s_addc_u32 s5, s77, s3
	v_mov_b64_e32 v[2:3], s[4:5]
	flat_load_dword v0, v[2:3] sc1
	s_waitcnt vmcnt(0) lgkmcnt(0)
	v_cmp_eq_u32_e32 vcc, v0, v1
	s_and_saveexec_b64 s[2:3], vcc
	s_cbranch_execz .LBB0_1933
	s_mov_b32 s23, 1
	s_mov_b64 s[8:9], 0
	s_branch .LBB0_1925
